# attention C loop: K/V ds_writes moved under the last PV MFMAs (unconditional), tail is only lgkmcnt(0)+barrier
# speedup vs baseline: 1.0068x; 1.0068x over previous
.LBB0_742:
	ds_read_b128 v[96:99], v240 offset:17408
	ds_read_b128 v[144:147], v240 offset:26112
	ds_read_b128 v[148:151], v240 offset:17440
	ds_read_b128 v[152:155], v240 offset:26144
	ds_read_b128 v[156:159], v240 offset:17472
	ds_read_b128 v[228:231], v240 offset:26176
	global_load_dwordx4 v[184:187], v247, s[100:101]
	global_load_dwordx4 v[188:191], v252, s[100:101]
	s_waitcnt lgkmcnt(5)
	v_mfma_f32_32x32x16_bf16 v[112:127], v[96:99], v[160:163], 0
	v_exp_f32_e32 v80, v80
	v_exp_f32_e32 v81, v81
	s_waitcnt lgkmcnt(4)
	v_mfma_f32_32x32x16_bf16 v[96:111], v[144:147], v[160:163], 0
	ds_read_b128 v[144:147], v240 offset:17504
	v_exp_f32_e32 v82, v82
	v_exp_f32_e32 v83, v83
	s_waitcnt lgkmcnt(4)
	v_mfma_f32_32x32x16_bf16 v[112:127], v[148:151], v[164:167], v[112:127]
	ds_read_b128 v[148:151], v240 offset:26208
	v_exp_f32_e32 v84, v84
	v_exp_f32_e32 v85, v85
	s_waitcnt lgkmcnt(4)
	v_mfma_f32_32x32x16_bf16 v[96:111], v[152:155], v[164:167], v[96:111]
	v_exp_f32_e32 v86, v86
	v_exp_f32_e32 v87, v87
	v_cvt_pk_bf16_f32 v128, v80, v81
	v_cvt_pk_bf16_f32 v129, v82, v83
	s_waitcnt lgkmcnt(3)
	v_mfma_f32_32x32x16_bf16 v[112:127], v[156:159], v[168:171], v[112:127]
	ds_read_b64_tr_b16 v[152:153], v207 offset:34816
	ds_read_b64_tr_b16 v[154:155], v207 offset:37376
	v_exp_f32_e32 v88, v88
	v_exp_f32_e32 v89, v89
	v_cvt_pk_bf16_f32 v130, v84, v85
	v_cvt_pk_bf16_f32 v131, v86, v87
	s_waitcnt lgkmcnt(4)
	v_mfma_f32_32x32x16_bf16 v[96:111], v[228:231], v[168:171], v[96:111]
	ds_read_b64_tr_b16 v[156:157], v207 offset:34880
	ds_read_b64_tr_b16 v[158:159], v207 offset:37440
	v_exp_f32_e32 v90, v90
	v_exp_f32_e32 v91, v91
	s_waitcnt lgkmcnt(5)
	v_mfma_f32_32x32x16_bf16 v[112:127], v[144:147], v[172:175], v[112:127]
	ds_read_b64_tr_b16 v[228:229], v207 offset:34944
	ds_read_b64_tr_b16 v[230:231], v207 offset:37504
	v_exp_f32_e32 v92, v92
	v_exp_f32_e32 v93, v93
	s_waitcnt lgkmcnt(6)
	v_mfma_f32_32x32x16_bf16 v[96:111], v[148:151], v[172:175], v[96:111]
	ds_read_b64_tr_b16 v[144:145], v207 offset:35008
	ds_read_b64_tr_b16 v[146:147], v207 offset:37568
	v_exp_f32_e32 v94, v94
	v_exp_f32_e32 v95, v95
	v_cvt_pk_bf16_f32 v132, v88, v89
	v_cvt_pk_bf16_f32 v133, v90, v91
	s_waitcnt lgkmcnt(6)
	v_mfma_f32_32x32x16_bf16 v[48:63], v[152:155], v[128:131], v[48:63]
	ds_read_b64_tr_b16 v[148:149], v207 offset:39936
	ds_read_b64_tr_b16 v[150:151], v207 offset:42496
	v_cvt_pk_bf16_f32 v134, v92, v93
	v_cvt_pk_bf16_f32 v135, v94, v95
	v_exp_f32_e32 v64, v64
	v_exp_f32_e32 v65, v65
	s_waitcnt lgkmcnt(6)
	v_mfma_f32_32x32x16_bf16 v[32:47], v[156:159], v[128:131], v[32:47]
	ds_read_b64_tr_b16 v[152:153], v207 offset:40000
	ds_read_b64_tr_b16 v[154:155], v207 offset:42560
	v_exp_f32_e32 v66, v66
	v_exp_f32_e32 v67, v67
	s_waitcnt lgkmcnt(6)
	v_mfma_f32_32x32x16_bf16 v[16:31], v[228:231], v[128:131], v[16:31]
	ds_read_b64_tr_b16 v[156:157], v207 offset:40064
	ds_read_b64_tr_b16 v[158:159], v207 offset:42624
	v_exp_f32_e32 v68, v68
	v_exp_f32_e32 v69, v69
	s_waitcnt lgkmcnt(6)
	v_mfma_f32_32x32x16_bf16 v[0:15], v[144:147], v[128:131], v[0:15]
	ds_read_b64_tr_b16 v[228:229], v207 offset:40128
	ds_read_b64_tr_b16 v[230:231], v207 offset:42688
	v_exp_f32_e32 v70, v70
	v_exp_f32_e32 v71, v71
	s_waitcnt lgkmcnt(6)
	v_mfma_f32_32x32x16_bf16 v[48:63], v[148:151], v[132:135], v[48:63]
	ds_read_b64_tr_b16 v[144:145], v207 offset:45056
	ds_read_b64_tr_b16 v[146:147], v207 offset:47616
	v_cvt_pk_bf16_f32 v136, v64, v65
	v_cvt_pk_bf16_f32 v137, v66, v67
	v_cvt_pk_bf16_f32 v138, v68, v69
	v_cvt_pk_bf16_f32 v139, v70, v71
	v_exp_f32_e32 v72, v72
	s_waitcnt lgkmcnt(6)
	v_mfma_f32_32x32x16_bf16 v[32:47], v[152:155], v[132:135], v[32:47]
	ds_read_b64_tr_b16 v[148:149], v207 offset:45120
	ds_read_b64_tr_b16 v[150:151], v207 offset:47680
	v_exp_f32_e32 v73, v73
	v_exp_f32_e32 v74, v74
	s_waitcnt lgkmcnt(6)
	v_mfma_f32_32x32x16_bf16 v[16:31], v[156:159], v[132:135], v[16:31]
	ds_read_b64_tr_b16 v[152:153], v207 offset:45184
	ds_read_b64_tr_b16 v[154:155], v207 offset:47744
	v_exp_f32_e32 v75, v75
	v_exp_f32_e32 v76, v76
	s_waitcnt lgkmcnt(6)
	v_mfma_f32_32x32x16_bf16 v[0:15], v[228:231], v[132:135], v[0:15]
	ds_read_b64_tr_b16 v[156:157], v207 offset:45248
	ds_read_b64_tr_b16 v[158:159], v207 offset:47808
	v_exp_f32_e32 v77, v77
	v_exp_f32_e32 v78, v78
	s_waitcnt lgkmcnt(6)
	v_mfma_f32_32x32x16_bf16 v[48:63], v[144:147], v[136:139], v[48:63]
	ds_read_b64_tr_b16 v[228:229], v207 offset:50176
	ds_read_b64_tr_b16 v[230:231], v207 offset:52736
	v_exp_f32_e32 v79, v79
	v_cvt_pk_bf16_f32 v140, v72, v73
	v_cvt_pk_bf16_f32 v141, v74, v75
	v_cvt_pk_bf16_f32 v142, v76, v77
	s_waitcnt lgkmcnt(6)
	v_mfma_f32_32x32x16_bf16 v[32:47], v[148:151], v[136:139], v[32:47]
	ds_read_b64_tr_b16 v[144:145], v207 offset:50240
	ds_read_b64_tr_b16 v[146:147], v207 offset:52800
	v_cvt_pk_bf16_f32 v143, v78, v79
	v_add_f32_e32 v80, v80, v82
	v_add_f32_e32 v81, v81, v83
	v_add_f32_e32 v84, v84, v86
	v_add_f32_e32 v85, v85, v87
	v_add_f32_e32 v88, v88, v90
	v_add_f32_e32 v89, v89, v91
	v_add_f32_e32 v92, v92, v94
	v_add_f32_e32 v93, v93, v95
	s_waitcnt lgkmcnt(6)
	v_mfma_f32_32x32x16_bf16 v[16:31], v[152:155], v[136:139], v[16:31]
	ds_read_b64_tr_b16 v[148:149], v207 offset:50304
	ds_read_b64_tr_b16 v[150:151], v207 offset:52864
	s_waitcnt vmcnt(3)
	ds_write_b128 v192, v[176:179]
	v_add_f32_e32 v64, v64, v66
	v_add_f32_e32 v65, v65, v67
	v_add_f32_e32 v68, v68, v70
	v_add_f32_e32 v69, v69, v71
	v_add_f32_e32 v72, v72, v74
	v_add_f32_e32 v73, v73, v75
	v_add_f32_e32 v76, v76, v78
	v_add_f32_e32 v77, v77, v79
	s_waitcnt lgkmcnt(7)
	v_mfma_f32_32x32x16_bf16 v[0:15], v[156:159], v[136:139], v[0:15]
	ds_read_b64_tr_b16 v[152:153], v207 offset:50368
	ds_read_b64_tr_b16 v[154:155], v207 offset:52928
	s_waitcnt vmcnt(2)
	ds_write_b128 v215, v[180:183]
	v_add_f32_e32 v80, v80, v84
	v_add_f32_e32 v81, v81, v85
	v_add_f32_e32 v88, v88, v92
	v_add_f32_e32 v89, v89, v93
	v_add_f32_e32 v64, v64, v68
	v_add_f32_e32 v65, v65, v69
	v_add_f32_e32 v72, v72, v76
	v_add_f32_e32 v73, v73, v77
	s_waitcnt lgkmcnt(8)
	v_mfma_f32_32x32x16_bf16 v[48:63], v[228:231], v[140:143], v[48:63]
	s_waitcnt vmcnt(1)
	ds_write_b128 v238, v[184:187] offset:55296
	v_add_f32_e32 v80, v80, v88
	v_add_f32_e32 v81, v81, v89
	v_add_f32_e32 v64, v64, v72
	v_add_f32_e32 v65, v65, v73
	s_waitcnt lgkmcnt(7)
	v_mfma_f32_32x32x16_bf16 v[32:47], v[144:147], v[140:143], v[32:47]
	s_waitcnt vmcnt(0)
	ds_write_b128 v239, v[188:191] offset:55296
	v_add_f32_e32 v64, v64, v80
	v_add_f32_e32 v65, v65, v81
	s_waitcnt lgkmcnt(6)
	v_mfma_f32_32x32x16_bf16 v[16:31], v[148:151], v[140:143], v[16:31]
	v_add_f32_e32 v64, v64, v65
	s_waitcnt lgkmcnt(3)
	v_mfma_f32_32x32x16_bf16 v[0:15], v[152:155], v[140:143], v[0:15]
	v_add_f32_e32 v246, v246, v64
.LBB0_746:
	s_cmp_gt_u32 s17, 28
	s_waitcnt lgkmcnt(0)
	s_barrier
	s_cbranch_scc1 .LBB0_748
	global_load_dwordx4 v[176:179], v253, s[98:99]
	global_load_dwordx4 v[180:183], v245, s[98:99]

.LBB0_751:
	s_waitcnt lgkmcnt(6)
	v_mfma_f32_32x32x16_bf16 v[48:63], v[152:155], v[128:131], v[48:63]
	ds_read_b64_tr_b16 v[148:149], v207 offset:60416
	ds_read_b64_tr_b16 v[150:151], v207 offset:62976
	v_cvt_pk_bf16_f32 v134, v124, v125
	v_cvt_pk_bf16_f32 v135, v126, v127
	v_exp_f32_e32 v96, v96
	v_exp_f32_e32 v97, v97
	s_waitcnt lgkmcnt(6)
	v_mfma_f32_32x32x16_bf16 v[32:47], v[156:159], v[128:131], v[32:47]
	ds_read_b64_tr_b16 v[152:153], v207 offset:60480
	ds_read_b64_tr_b16 v[154:155], v207 offset:63040
	v_exp_f32_e32 v98, v98
	v_exp_f32_e32 v99, v99
	s_waitcnt lgkmcnt(6)
	v_mfma_f32_32x32x16_bf16 v[16:31], v[228:231], v[128:131], v[16:31]
	ds_read_b64_tr_b16 v[156:157], v207 offset:60544
	ds_read_b64_tr_b16 v[158:159], v207 offset:63104
	v_exp_f32_e32 v100, v100
	v_exp_f32_e32 v101, v101
	s_waitcnt lgkmcnt(6)
	v_mfma_f32_32x32x16_bf16 v[0:15], v[144:147], v[128:131], v[0:15]
	ds_read_b64_tr_b16 v[228:229], v207 offset:60608
	ds_read_b64_tr_b16 v[230:231], v207 offset:63168
	v_exp_f32_e32 v102, v102
	v_exp_f32_e32 v103, v103
	s_waitcnt lgkmcnt(6)
	v_mfma_f32_32x32x16_bf16 v[48:63], v[148:151], v[132:135], v[48:63]
	ds_read_b64_tr_b16 v[144:145], v209 offset:10240
	ds_read_b64_tr_b16 v[146:147], v209 offset:12800
	v_cvt_pk_bf16_f32 v136, v96, v97
	v_cvt_pk_bf16_f32 v137, v98, v99
	v_cvt_pk_bf16_f32 v138, v100, v101
	v_cvt_pk_bf16_f32 v139, v102, v103
	v_exp_f32_e32 v104, v104
	s_waitcnt lgkmcnt(6)
	v_mfma_f32_32x32x16_bf16 v[32:47], v[152:155], v[132:135], v[32:47]
	ds_read_b64_tr_b16 v[148:149], v209 offset:10304
	ds_read_b64_tr_b16 v[150:151], v209 offset:12864
	v_exp_f32_e32 v105, v105
	v_exp_f32_e32 v106, v106
	s_waitcnt lgkmcnt(6)
	v_mfma_f32_32x32x16_bf16 v[16:31], v[156:159], v[132:135], v[16:31]
	ds_read_b64_tr_b16 v[152:153], v209 offset:10368
	ds_read_b64_tr_b16 v[154:155], v209 offset:12928
	v_exp_f32_e32 v107, v107
	v_exp_f32_e32 v108, v108
	s_waitcnt lgkmcnt(6)
	v_mfma_f32_32x32x16_bf16 v[0:15], v[228:231], v[132:135], v[0:15]
	ds_read_b64_tr_b16 v[156:157], v209 offset:10432
	ds_read_b64_tr_b16 v[158:159], v209 offset:12992
	v_exp_f32_e32 v109, v109
	v_exp_f32_e32 v110, v110
	s_waitcnt lgkmcnt(6)
	v_mfma_f32_32x32x16_bf16 v[48:63], v[144:147], v[136:139], v[48:63]
	ds_read_b64_tr_b16 v[228:229], v209 offset:15360
	ds_read_b64_tr_b16 v[230:231], v209 offset:17920
	v_exp_f32_e32 v111, v111
	v_cvt_pk_bf16_f32 v140, v104, v105
	v_cvt_pk_bf16_f32 v141, v106, v107
	v_cvt_pk_bf16_f32 v142, v108, v109
	s_waitcnt lgkmcnt(6)
	v_mfma_f32_32x32x16_bf16 v[32:47], v[148:151], v[136:139], v[32:47]
	ds_read_b64_tr_b16 v[144:145], v209 offset:15424
	ds_read_b64_tr_b16 v[146:147], v209 offset:17984
	v_cvt_pk_bf16_f32 v143, v110, v111
	v_add_f32_e32 v112, v112, v114
	v_add_f32_e32 v113, v113, v115
	v_add_f32_e32 v116, v116, v118
	v_add_f32_e32 v117, v117, v119
	v_add_f32_e32 v120, v120, v122
	v_add_f32_e32 v121, v121, v123
	v_add_f32_e32 v124, v124, v126
	v_add_f32_e32 v125, v125, v127
	s_waitcnt lgkmcnt(6)
	v_mfma_f32_32x32x16_bf16 v[16:31], v[152:155], v[136:139], v[16:31]
	ds_read_b64_tr_b16 v[148:149], v209 offset:15488
	ds_read_b64_tr_b16 v[150:151], v209 offset:18048
	s_waitcnt vmcnt(3)
	ds_write_b128 v241, v[176:179] offset:17408
	v_add_f32_e32 v96, v96, v98
	v_add_f32_e32 v97, v97, v99
	v_add_f32_e32 v100, v100, v102
	v_add_f32_e32 v101, v101, v103
	v_add_f32_e32 v104, v104, v106
	v_add_f32_e32 v105, v105, v107
	v_add_f32_e32 v108, v108, v110
	v_add_f32_e32 v109, v109, v111
	s_waitcnt lgkmcnt(7)
	v_mfma_f32_32x32x16_bf16 v[0:15], v[156:159], v[136:139], v[0:15]
	ds_read_b64_tr_b16 v[152:153], v209 offset:15552
	ds_read_b64_tr_b16 v[154:155], v209 offset:18112
	s_waitcnt vmcnt(2)
	ds_write_b128 v242, v[180:183] offset:17408
	v_add_f32_e32 v112, v112, v116
	v_add_f32_e32 v113, v113, v117
	v_add_f32_e32 v120, v120, v124
	v_add_f32_e32 v121, v121, v125
	v_add_f32_e32 v96, v96, v100
	v_add_f32_e32 v97, v97, v101
	v_add_f32_e32 v104, v104, v108
	v_add_f32_e32 v105, v105, v109
	s_waitcnt lgkmcnt(8)
	v_mfma_f32_32x32x16_bf16 v[48:63], v[228:231], v[140:143], v[48:63]
	s_waitcnt vmcnt(1)
	ds_write_b128 v243, v[184:187] offset:34816
	v_add_f32_e32 v112, v112, v120
	v_add_f32_e32 v113, v113, v121
	v_add_f32_e32 v96, v96, v104
	v_add_f32_e32 v97, v97, v105
	s_waitcnt lgkmcnt(7)
	v_mfma_f32_32x32x16_bf16 v[32:47], v[144:147], v[140:143], v[32:47]
	s_waitcnt vmcnt(0)
	ds_write_b128 v244, v[188:191] offset:34816
	v_add_f32_e32 v96, v96, v112
	v_add_f32_e32 v97, v97, v113
	s_waitcnt lgkmcnt(6)
	v_mfma_f32_32x32x16_bf16 v[16:31], v[148:151], v[140:143], v[16:31]
	v_add_f32_e32 v96, v96, v97
	s_waitcnt lgkmcnt(3)
	v_mfma_f32_32x32x16_bf16 v[0:15], v[152:155], v[140:143], v[0:15]
	v_add_f32_e32 v246, v246, v96
.LBB0_755:
.LBB0_757:
	s_add_u32 s18, s18, 0x20000
	s_addc_u32 s19, s19, 0
	s_add_i32 s20, s17, 2
	s_cmp_lt_u32 s17, 29
	s_waitcnt lgkmcnt(0)
	s_barrier
	s_cbranch_scc0 .LBB0_759
	s_add_u32 s98, s98, 0x20000
	s_addc_u32 s99, s99, 0
	s_add_u32 s100, s100, 0x20000
	s_addc_u32 s101, s101, 0
	s_mov_b32 s17, s20
	s_branch .LBB0_740
